# PA: start the CUs of each XCD in 4 groups 6.4us apart so epilogue store bursts do not coincide
# baseline (speedup 1.0000x reference)
.LBB0_267:
	s_and_b64 vcc, exec, s[0:1]
	s_cbranch_vccz .LBB0_420
	v_readlane_b32 s0, v251, 22
	v_mov_b32_e32 v5, v167
	v_readlane_b32 s1, v251, 23
	s_andn2_b64 vcc, exec, s[0:1]
	v_readfirstlane_b32 s10, v5
	s_cbranch_vccnz .LBB0_419
	s_lshr_b32 s0, s57, 3
	s_and_b32 s0, s0, 3
	s_mul_i32 s0, s0, 2
	s_cmp_eq_u32 s0, 0
	s_cbranch_scc1 .Lstg_done
.Lstg_loop:
	s_sleep 100
	s_sub_u32 s0, s0, 1
	s_cmp_lg_u32 s0, 0
	s_cbranch_scc1 .Lstg_loop
.Lstg_done:
	v_lshlrev_b32_e32 v0, 4, v5
	s_waitcnt lgkmcnt(0)
	v_add_u32_e32 v1, 0x2000, v0
	v_ashrrev_i32_e32 v2, 31, v1
	v_lshrrev_b32_e32 v2, 22, v2
	v_add_u32_e32 v2, v1, v2
	v_ashrrev_i32_e32 v4, 10, v2
	v_mul_i32_i24_e32 v2, 0x400, v4
	v_sub_u32_e32 v1, v1, v2
	v_lshrrev_b32_e32 v2, 4, v1
	v_bitop3_b32 v1, v2, v1, 32 bitop3:0x6c
	v_ashrrev_i32_e32 v2, 31, v1
	v_readlane_b32 s0, v254, 62
	v_lshrrev_b32_e32 v2, 26, v2
	v_readlane_b32 s1, v254, 63
	v_add_u32_e32 v2, v1, v2
	v_lshlrev_b32_e32 v3, 3, v4
	s_ashr_i32 s1, s0, 31
	v_ashrrev_i32_e32 v6, 6, v2
	v_and_b32_e32 v3, -16, v3
	s_lshl_b64 s[0:1], s[0:1], 24
	v_readlane_b32 s8, v251, 12
	v_add_u32_e32 v3, v6, v3
	s_add_u32 s14, s8, s0
	v_and_b32_e32 v7, 3, v6
	s_mov_b32 s0, 0x1fffe0
	s_waitcnt vmcnt(0)
	v_lshrrev_b32_e32 v8, 2, v3
	v_lshlrev_b32_e32 v9, 1, v3
	v_and_b32_e32 v2, 0xc0, v2
	v_and_or_b32 v7, v3, s0, v7
	v_and_b32_e32 v8, 4, v8
	v_and_b32_e32 v9, 24, v9
	v_sub_u32_e32 v1, v1, v2
	v_mov_b32_e32 v12, 1
	v_or3_b32 v8, v7, v8, v9
	v_lshlrev_b32_e32 v7, 5, v4
	v_ashrrev_i16_sdwa v1, v12, sext(v1) dst_sel:DWORD dst_unused:UNUSED_PAD src0_sel:DWORD src1_sel:BYTE_0
	v_and_b32_e32 v9, 32, v7
	v_bfe_i32 v7, v1, 0, 16
	v_add_lshl_u32 v1, v9, v7, 1
	v_lshl_add_u32 v148, v8, 11, v1
	v_lshl_add_u32 v150, v3, 11, v1
	v_bfe_i32 v1, v5, 27, 1
	v_lshrrev_b32_e32 v1, 22, v1
	v_add_u32_e32 v1, v0, v1
	v_and_b32_e32 v1, 0xfffffc00, v1
	v_sub_u32_e32 v0, v0, v1
	v_lshrrev_b32_e32 v1, 4, v0
	v_ashrrev_i32_e32 v2, 31, v5
	v_bitop3_b32 v0, v1, v0, 32 bitop3:0x6c
	v_lshrrev_b32_e32 v2, 26, v2
	v_ashrrev_i32_e32 v1, 31, v0
	v_add_u32_e32 v2, v5, v2
	v_lshrrev_b32_e32 v1, 26, v1
	v_ashrrev_i32_e32 v9, 6, v2
	v_add_u32_e32 v1, v0, v1
	v_lshlrev_b32_e32 v2, 3, v9
	v_ashrrev_i32_e32 v8, 6, v1
	v_and_b32_e32 v2, -16, v2
	v_add_u32_e32 v2, v8, v2
	v_and_b32_e32 v3, 3, v8
	v_lshrrev_b32_e32 v10, 2, v2
	v_lshlrev_b32_e32 v11, 1, v2
	v_and_b32_e32 v1, 0xc0, v1
	v_readlane_b32 s9, v251, 13
	v_and_or_b32 v3, v2, s0, v3
	v_and_b32_e32 v10, 4, v10
	v_and_b32_e32 v11, 24, v11
	v_sub_u32_e32 v0, v0, v1
	s_addc_u32 s15, s9, s1
	s_ashr_i32 s11, s10, 6
	v_or3_b32 v3, v3, v10, v11
	v_lshlrev_b32_e32 v10, 5, v9
	v_ashrrev_i16_sdwa v0, v12, sext(v0) dst_sel:DWORD dst_unused:UNUSED_PAD src0_sel:DWORD src1_sel:BYTE_0
	s_lshl_b32 s16, s11, 10
	v_and_b32_e32 v11, 32, v10
	v_bfe_i32 v10, v0, 0, 16
	v_add_lshl_u32 v0, v11, v10, 1
	s_add_i32 s17, s16, 16
	v_readlane_b32 s0, v253, 56
	v_lshl_add_u32 v152, v3, 11, v0
	s_add_i32 m0, s17, 0x10000
	v_readlane_b32 s1, v253, 57
	s_ashr_i32 s12, s10, 8
	v_lshl_add_u32 v154, v2, 11, v0
	v_mov_b32_e32 v155, v157
	v_mov_b32_e32 v151, v157
	s_nop 0
	global_load_lds_dwordx4 v152, s[0:1]
	s_add_i32 m0, s17, 0x12000
	s_nop 0
	global_load_lds_dwordx4 v148, s[0:1]
	v_readlane_b32 s0, v253, 54
	s_add_i32 m0, s17, 0x14000
	v_readlane_b32 s1, v253, 55
	s_nop 4
	global_load_lds_dwordx4 v152, s[0:1]
	s_add_i32 m0, s17, 0x16000
	s_nop 0
	global_load_lds_dwordx4 v148, s[0:1]
	v_readlane_b32 s0, v253, 51
	v_readlane_b32 s1, v253, 52
	s_add_u32 s8, s14, s0
	s_addc_u32 s9, s15, s1
	s_add_i32 s18, s17, 0x2000
	s_mov_b32 m0, s17
	s_add_u32 s0, s8, 0x40000
	global_load_lds_dwordx4 v154, s[8:9]
	s_mov_b32 m0, s18
	s_addc_u32 s1, s9, 0
	s_add_i32 s19, s17, 0x4000
	global_load_lds_dwordx4 v150, s[8:9]
	s_mov_b32 m0, s19
	s_add_i32 s20, s17, 0x6000
	global_load_lds_dwordx4 v154, s[0:1]
	s_mov_b32 m0, s20
	s_cmp_eq_u32 s12, 1
	global_load_lds_dwordx4 v150, s[0:1]
	v_lshl_add_u64 v[0:1], s[8:9], 0, v[154:155]
	s_cselect_b64 s[0:1], -1, 0
	s_cmp_lg_u32 s12, 1
	v_lshl_add_u64 v[2:3], s[8:9], 0, v[150:151]
	s_cbranch_scc1 .LBB0_271
	s_barrier
